# P5 H2 write-out: next group's LDS reads issued right after the current group's FMAs
# baseline (speedup 1.0000x reference)
.Lp5n_nosm:
	ds_read_b128 v[242:245], v230 offset:0
	ds_read_b128 v[246:249], v230 offset:16
	ds_read_b128 v[250:253], v230 offset:4096
	ds_read_b128 v[180:183], v230 offset:4112
	s_waitcnt lgkmcnt(0)
	v_pk_mul_f32 v[184:185], v[152:153], v[64:65] op_sel_hi:[1,0]
	v_pk_mul_f32 v[186:187], v[154:155], v[64:65] op_sel_hi:[1,0]
	v_pk_mul_f32 v[188:189], v[148:149], v[64:65] op_sel_hi:[1,0]
	v_pk_mul_f32 v[190:191], v[150:151], v[64:65] op_sel_hi:[1,0]
	v_pk_fma_f32 v[184:185], v[242:243], v[184:185], v[250:251]
	v_pk_fma_f32 v[186:187], v[244:245], v[186:187], v[252:253]
	v_pk_fma_f32 v[188:189], v[246:247], v[188:189], v[180:181]
	v_pk_fma_f32 v[190:191], v[248:249], v[190:191], v[182:183]
	ds_read_b128 v[242:245], v230 offset:128
	ds_read_b128 v[246:249], v230 offset:144
	ds_read_b128 v[250:253], v230 offset:4224
	ds_read_b128 v[180:183], v230 offset:4240
	v_cvt_pk_bf16_f32 v184, v184, v185
	v_cvt_pk_bf16_f32 v185, v186, v187
	v_cvt_pk_bf16_f32 v186, v188, v189
	v_cvt_pk_bf16_f32 v187, v190, v191
	global_store_dwordx4 v[238:239], v[184:187], off offset:0
	s_nop 1
	s_waitcnt lgkmcnt(0)
	v_pk_mul_f32 v[184:185], v[160:161], v[64:65] op_sel_hi:[1,0]
	v_pk_mul_f32 v[186:187], v[162:163], v[64:65] op_sel_hi:[1,0]
	v_pk_mul_f32 v[188:189], v[156:157], v[64:65] op_sel_hi:[1,0]
	v_pk_mul_f32 v[190:191], v[158:159], v[64:65] op_sel_hi:[1,0]
	v_pk_fma_f32 v[184:185], v[242:243], v[184:185], v[250:251]
	v_pk_fma_f32 v[186:187], v[244:245], v[186:187], v[252:253]
	v_pk_fma_f32 v[188:189], v[246:247], v[188:189], v[180:181]
	v_pk_fma_f32 v[190:191], v[248:249], v[190:191], v[182:183]
	ds_read_b128 v[242:245], v230 offset:256
	ds_read_b128 v[246:249], v230 offset:272
	ds_read_b128 v[250:253], v230 offset:4352
	ds_read_b128 v[180:183], v230 offset:4368
	v_cvt_pk_bf16_f32 v184, v184, v185
	v_cvt_pk_bf16_f32 v185, v186, v187
	v_cvt_pk_bf16_f32 v186, v188, v189
	v_cvt_pk_bf16_f32 v187, v190, v191
	global_store_dwordx4 v[238:239], v[184:187], off offset:64
	s_nop 1
	s_waitcnt lgkmcnt(0)
	v_pk_mul_f32 v[184:185], v[168:169], v[64:65] op_sel_hi:[1,0]
	v_pk_mul_f32 v[186:187], v[170:171], v[64:65] op_sel_hi:[1,0]
	v_pk_mul_f32 v[188:189], v[164:165], v[64:65] op_sel_hi:[1,0]
	v_pk_mul_f32 v[190:191], v[166:167], v[64:65] op_sel_hi:[1,0]
	v_pk_fma_f32 v[184:185], v[242:243], v[184:185], v[250:251]
	v_pk_fma_f32 v[186:187], v[244:245], v[186:187], v[252:253]
	v_pk_fma_f32 v[188:189], v[246:247], v[188:189], v[180:181]
	v_pk_fma_f32 v[190:191], v[248:249], v[190:191], v[182:183]
	ds_read_b128 v[242:245], v230 offset:384
	ds_read_b128 v[246:249], v230 offset:400
	ds_read_b128 v[250:253], v230 offset:4480
	ds_read_b128 v[180:183], v230 offset:4496
	v_cvt_pk_bf16_f32 v184, v184, v185
	v_cvt_pk_bf16_f32 v185, v186, v187
	v_cvt_pk_bf16_f32 v186, v188, v189
	v_cvt_pk_bf16_f32 v187, v190, v191
	global_store_dwordx4 v[238:239], v[184:187], off offset:128
	s_nop 1
	s_waitcnt lgkmcnt(0)
	v_pk_mul_f32 v[184:185], v[176:177], v[64:65] op_sel_hi:[1,0]
	v_pk_mul_f32 v[186:187], v[178:179], v[64:65] op_sel_hi:[1,0]
	v_pk_mul_f32 v[188:189], v[172:173], v[64:65] op_sel_hi:[1,0]
	v_pk_mul_f32 v[190:191], v[174:175], v[64:65] op_sel_hi:[1,0]
	v_pk_fma_f32 v[184:185], v[242:243], v[184:185], v[250:251]
	v_pk_fma_f32 v[186:187], v[244:245], v[186:187], v[252:253]
	v_pk_fma_f32 v[188:189], v[246:247], v[188:189], v[180:181]
	v_pk_fma_f32 v[190:191], v[248:249], v[190:191], v[182:183]
	ds_read_b128 v[242:245], v230 offset:512
	ds_read_b128 v[246:249], v230 offset:528
	ds_read_b128 v[250:253], v230 offset:4608
	ds_read_b128 v[180:183], v230 offset:4624
	v_cvt_pk_bf16_f32 v184, v184, v185
	v_cvt_pk_bf16_f32 v185, v186, v187
	v_cvt_pk_bf16_f32 v186, v188, v189
	v_cvt_pk_bf16_f32 v187, v190, v191
	global_store_dwordx4 v[238:239], v[184:187], off offset:192
	s_nop 1
	s_waitcnt lgkmcnt(0)
	v_pk_mul_f32 v[184:185], v[200:201], v[64:65] op_sel_hi:[1,0]
	v_pk_mul_f32 v[186:187], v[202:203], v[64:65] op_sel_hi:[1,0]
	v_pk_mul_f32 v[188:189], v[196:197], v[64:65] op_sel_hi:[1,0]
	v_pk_mul_f32 v[190:191], v[198:199], v[64:65] op_sel_hi:[1,0]
	v_pk_fma_f32 v[184:185], v[242:243], v[184:185], v[250:251]
	v_pk_fma_f32 v[186:187], v[244:245], v[186:187], v[252:253]
	v_pk_fma_f32 v[188:189], v[246:247], v[188:189], v[180:181]
	v_pk_fma_f32 v[190:191], v[248:249], v[190:191], v[182:183]
	ds_read_b128 v[242:245], v230 offset:640
	ds_read_b128 v[246:249], v230 offset:656
	ds_read_b128 v[250:253], v230 offset:4736
	ds_read_b128 v[180:183], v230 offset:4752
	v_cvt_pk_bf16_f32 v184, v184, v185
	v_cvt_pk_bf16_f32 v185, v186, v187
	v_cvt_pk_bf16_f32 v186, v188, v189
	v_cvt_pk_bf16_f32 v187, v190, v191
	global_store_dwordx4 v[238:239], v[184:187], off offset:256
	s_nop 1
	s_waitcnt lgkmcnt(0)
	v_pk_mul_f32 v[184:185], v[208:209], v[64:65] op_sel_hi:[1,0]
	v_pk_mul_f32 v[186:187], v[210:211], v[64:65] op_sel_hi:[1,0]
	v_pk_mul_f32 v[188:189], v[204:205], v[64:65] op_sel_hi:[1,0]
	v_pk_mul_f32 v[190:191], v[206:207], v[64:65] op_sel_hi:[1,0]
	v_pk_fma_f32 v[184:185], v[242:243], v[184:185], v[250:251]
	v_pk_fma_f32 v[186:187], v[244:245], v[186:187], v[252:253]
	v_pk_fma_f32 v[188:189], v[246:247], v[188:189], v[180:181]
	v_pk_fma_f32 v[190:191], v[248:249], v[190:191], v[182:183]
	ds_read_b128 v[242:245], v230 offset:768
	ds_read_b128 v[246:249], v230 offset:784
	ds_read_b128 v[250:253], v230 offset:4864
	ds_read_b128 v[180:183], v230 offset:4880
	v_cvt_pk_bf16_f32 v184, v184, v185
	v_cvt_pk_bf16_f32 v185, v186, v187
	v_cvt_pk_bf16_f32 v186, v188, v189
	v_cvt_pk_bf16_f32 v187, v190, v191
	global_store_dwordx4 v[238:239], v[184:187], off offset:320
	s_nop 1
	s_waitcnt lgkmcnt(0)
	v_pk_mul_f32 v[184:185], v[212:213], v[64:65] op_sel_hi:[1,0]
	v_pk_mul_f32 v[186:187], v[214:215], v[64:65] op_sel_hi:[1,0]
	v_pk_mul_f32 v[188:189], v[216:217], v[64:65] op_sel_hi:[1,0]
	v_pk_mul_f32 v[190:191], v[218:219], v[64:65] op_sel_hi:[1,0]
	v_pk_fma_f32 v[184:185], v[242:243], v[184:185], v[250:251]
	v_pk_fma_f32 v[186:187], v[244:245], v[186:187], v[252:253]
	v_pk_fma_f32 v[188:189], v[246:247], v[188:189], v[180:181]
	v_pk_fma_f32 v[190:191], v[248:249], v[190:191], v[182:183]
	ds_read_b128 v[242:245], v230 offset:896
	ds_read_b128 v[246:249], v230 offset:912
	ds_read_b128 v[250:253], v230 offset:4992
	ds_read_b128 v[180:183], v230 offset:5008
	v_cvt_pk_bf16_f32 v184, v184, v185
	v_cvt_pk_bf16_f32 v185, v186, v187
	v_cvt_pk_bf16_f32 v186, v188, v189
	v_cvt_pk_bf16_f32 v187, v190, v191
	global_store_dwordx4 v[238:239], v[184:187], off offset:384
	s_nop 1
	s_waitcnt lgkmcnt(0)
	v_pk_mul_f32 v[184:185], v[224:225], v[64:65] op_sel_hi:[1,0]
	v_pk_mul_f32 v[186:187], v[226:227], v[64:65] op_sel_hi:[1,0]
	v_pk_mul_f32 v[188:189], v[220:221], v[64:65] op_sel_hi:[1,0]
	v_pk_mul_f32 v[190:191], v[222:223], v[64:65] op_sel_hi:[1,0]
	v_pk_fma_f32 v[184:185], v[242:243], v[184:185], v[250:251]
	v_pk_fma_f32 v[186:187], v[244:245], v[186:187], v[252:253]
	v_pk_fma_f32 v[188:189], v[246:247], v[188:189], v[180:181]
	v_pk_fma_f32 v[190:191], v[248:249], v[190:191], v[182:183]
	v_cvt_pk_bf16_f32 v184, v184, v185
	v_cvt_pk_bf16_f32 v185, v186, v187
	v_cvt_pk_bf16_f32 v186, v188, v189
	v_cvt_pk_bf16_f32 v187, v190, v191
	global_store_dwordx4 v[238:239], v[184:187], off offset:448
	s_nop 1
	v_xor_b32_e32 v231, 0x8000, v231
	v_xor_b32_e32 v232, 0x8000, v232
	v_xor_b32_e32 v233, 0x8000, v233
	v_xor_b32_e32 v234, 0x8000, v234
	s_add_i32 s98, s98, 1
	s_cmp_lt_u32 s98, 8
	s_cbranch_scc1 .Lp5n_loop
	s_lshl_b32 s61, s100, 2
	s_add_i32 s61, s61, s99
	s_lshl_b32 s61, s61, 1
	s_lshl_b32 s62, s61, 4
	s_lshl_b32 s101, s94, 8
	s_add_i32 s62, s62, s101
	v_or_b32_e32 v130, s62, v120
	s_add_i32 s94, s94, s82
	s_add_i32 s62, s62, s63
	s_cmpk_gt_i32 s94, 0xff
	v_add_u32_e32 v130, s63, v130
	s_cbranch_scc0 .LBB0_738
